# final RMSNorm phase row loop software-pipelined with two register sets (next-but-one row's loads issued after the stores of the same set) on top of the GEMM2-tail overlap
# baseline (speedup 1.0000x reference)
; __device__ __forceinline__ void phase_final(const Params& p) {
;     const int tid = threadIdx.x, lane = tid & 63, wid = tid >> 6;
;     f32x4 fg0[4], fg1[4];
; #pragma unroll
;     for (int i = 0; i < 4; ++i) { const int c = i * 512 + lane * 8; fg0[i] = *(const f32x4*)(p.final_g + c); fg1[i] = *(const f32x4*)(p.final_g + c + 4); }
;     for (int row = blockIdx.x * 8 + wid; row < MT; row += gridDim.x * 8) {
;         const bf16_t* yr = p.QG + (size_t)row * DM; float* xr = p.out + (size_t)row * DM; const float* xi = xrow(p, row);
;         u32x4 v[4]; f32x4 y0[4], y1[4]; float ss = 0.f;
; #pragma unroll
;         for (int i = 0; i < 4; ++i) { const int c = i * 512 + lane * 8; v[i] = *(const u32x4*)(yr + c); y0[i] = *(const f32x4*)(xi + c); y1[i] = *(const f32x4*)(xi + c + 4); }
.Lfin1_sync:
	s_barrier
	s_load_dwordx4 s[4:7], s[0:1], 0xa8
	s_load_dwordx4 s[8:11], s[0:1], 0x0
	v_and_b32_e32 v36, 0x1f8, v131
	v_lshlrev_b32_e32 v16, 2, v36
	v_or_b32_e32 v38, 0x400, v36
	s_waitcnt lgkmcnt(0)
	global_load_dwordx4 v[0:3], v16, s[4:5] offset:16
	global_load_dwordx4 v[4:7], v16, s[4:5]
	global_load_dwordx4 v[8:11], v16, s[4:5] offset:2064
	global_load_dwordx4 v[12:15], v16, s[4:5] offset:2048
	v_or_b32_e32 v46, 0x600, v36
	v_lshlrev_b32_e32 v24, 2, v38
	v_lshlrev_b32_e32 v32, 2, v46
	global_load_dwordx4 v[16:19], v24, s[4:5] offset:16
	global_load_dwordx4 v[20:23], v24, s[4:5]
	s_nop 0
	global_load_dwordx4 v[24:27], v32, s[4:5] offset:16
	global_load_dwordx4 v[28:31], v32, s[4:5]
	v_mbcnt_hi_u32_b32 v32, -1, v129
	v_and_b32_e32 v34, 64, v32
	v_add_u32_e32 v34, 64, v34
	v_xor_b32_e32 v35, 32, v32
	v_cmp_lt_i32_e32 vcc, v35, v34
	s_load_dwordx2 s[48:49], s[0:1], 0xe8
	v_mov_b32_e32 v33, 0
	v_cndmask_b32_e32 v35, v32, v35, vcc
	v_lshlrev_b32_e32 v40, 2, v35
	v_xor_b32_e32 v35, 16, v32
	v_cmp_lt_i32_e32 vcc, v35, v34
	s_mov_b32 s3, 0x8000
	v_cndmask_b32_e32 v35, v32, v35, vcc
	v_lshlrev_b32_e32 v41, 2, v35
	v_xor_b32_e32 v35, 8, v32
	v_cmp_lt_i32_e32 vcc, v35, v34
	s_mov_b32 s4, 0x800000
	s_mov_b32 s5, 0x87ff
	v_cndmask_b32_e32 v35, v32, v35, vcc
	v_lshlrev_b32_e32 v42, 2, v35
	v_xor_b32_e32 v35, 4, v32
	v_cmp_lt_i32_e32 vcc, v35, v34
	s_nop 1
	v_cndmask_b32_e32 v35, v32, v35, vcc
	v_lshlrev_b32_e32 v43, 2, v35
	v_xor_b32_e32 v35, 2, v32
	v_cmp_lt_i32_e32 vcc, v35, v34
	s_nop 1
	v_cndmask_b32_e32 v35, v32, v35, vcc
	v_lshlrev_b32_e32 v44, 2, v35
	v_xor_b32_e32 v35, 1, v32
	v_cmp_lt_i32_e32 vcc, v35, v34
	s_nop 1
	v_cndmask_b32_e32 v32, v32, v35, vcc
	v_lshlrev_b32_e32 v45, 2, v32
	v_lshlrev_b32_e32 v32, 1, v36
	s_waitcnt lgkmcnt(0)
	v_lshl_add_u64 v[34:35], s[48:49], 0, v[32:33]
	v_lshlrev_b32_e32 v32, 2, v36
	v_lshlrev_b32_e32 v36, 2, v38
	v_lshlrev_b32_e32 v38, 2, v46
	v_mov_b32_e32 v46, 0x358637bd
	v_mov_b32_e32 v37, 0
	v_mov_b32_e32 v39, 0
	s_lshr_b32 s44, s42, 6
	s_lshl_b32 s45, s40, 3
	s_add_i32 s44, s45, s44
	s_add_i32 s44, s44, 0xfffffe00
	s_add_i32 s45, s44, 0x600
	s_lshr_b32 s46, s44, 11
	s_max_u32 s46, s46, 1
	s_add_i32 s46, s46, -1
	s_lshl_b32 s46, s46, 11
	s_add_i32 s46, s46, s44
	v_mov_b32_e32 v110, s46
	v_ashrrev_i32_e32 v111, 31, v110
	v_add_u32_e32 v100, 0xffff8000, v110
	v_cmp_gt_i32_e32 vcc, s3, v110
	v_lshlrev_b64 v[48:49], 12, v[110:111]
	v_mov_b32_e32 v101, s11
	v_mov_b32_e32 v47, s9
	v_mov_b32_e32 v64, s10
	v_mov_b32_e32 v66, s8
	v_cndmask_b32_e32 v63, 0, v111, vcc
	v_cndmask_b32_e32 v62, v100, v110, vcc
	v_lshl_add_u64 v[60:61], v[34:35], 0, v[48:49]
	v_cndmask_b32_e32 v65, v101, v47, vcc
	v_cndmask_b32_e32 v64, v64, v66, vcc
	v_lshlrev_b64 v[66:67], 13, v[62:63]
	global_load_dwordx4 v[48:51], v[60:61], off
	global_load_dwordx4 v[52:55], v[60:61], off offset:1024
	v_lshl_add_u64 v[88:89], v[64:65], 0, v[66:67]
	v_lshl_add_u64 v[80:81], v[88:89], 0, v[32:33]
	global_load_dwordx4 v[56:59], v[60:61], off offset:2048
	global_load_dwordx4 v[60:63], v[60:61], off offset:3072
	s_nop 0
	global_load_dwordx4 v[64:67], v[80:81], off
	global_load_dwordx4 v[68:71], v[80:81], off offset:16
	global_load_dwordx4 v[72:75], v[80:81], off offset:2048
	global_load_dwordx4 v[76:79], v[80:81], off offset:2064
	v_lshl_add_u64 v[90:91], v[88:89], 0, v[36:37]
	global_load_dwordx4 v[80:83], v[90:91], off
	global_load_dwordx4 v[84:87], v[90:91], off offset:16
	v_lshl_add_u64 v[96:97], v[88:89], 0, v[38:39]
	global_load_dwordx4 v[88:91], v[96:97], off
	global_load_dwordx4 v[92:95], v[96:97], off offset:16
	s_lshr_b32 s46, s45, 11
	s_max_u32 s46, s46, 1
	s_add_i32 s46, s46, -1
	s_lshl_b32 s46, s46, 11
	s_add_i32 s46, s46, s45
	v_mov_b32_e32 v210, s46
	v_ashrrev_i32_e32 v211, 31, v210
	v_add_u32_e32 v200, 0xffff8000, v210
	v_cmp_gt_i32_e32 vcc, s3, v210
	v_lshlrev_b64 v[148:149], 12, v[210:211]
	v_mov_b32_e32 v201, s11
	v_mov_b32_e32 v147, s9
	v_mov_b32_e32 v164, s10
	v_mov_b32_e32 v166, s8
	v_cndmask_b32_e32 v163, 0, v211, vcc
	v_cndmask_b32_e32 v162, v200, v210, vcc
	v_lshl_add_u64 v[160:161], v[34:35], 0, v[148:149]
	v_cndmask_b32_e32 v165, v201, v147, vcc
	v_cndmask_b32_e32 v164, v164, v166, vcc
	v_lshlrev_b64 v[166:167], 13, v[162:163]
	global_load_dwordx4 v[148:151], v[160:161], off
	global_load_dwordx4 v[152:155], v[160:161], off offset:1024
	v_lshl_add_u64 v[188:189], v[164:165], 0, v[166:167]
	v_lshl_add_u64 v[180:181], v[188:189], 0, v[32:33]
	global_load_dwordx4 v[156:159], v[160:161], off offset:2048
	global_load_dwordx4 v[160:163], v[160:161], off offset:3072
	s_nop 0
	global_load_dwordx4 v[164:167], v[180:181], off
	global_load_dwordx4 v[168:171], v[180:181], off offset:16
	global_load_dwordx4 v[172:175], v[180:181], off offset:2048
	global_load_dwordx4 v[176:179], v[180:181], off offset:2064
	v_lshl_add_u64 v[190:191], v[188:189], 0, v[36:37]
	global_load_dwordx4 v[180:183], v[190:191], off
	global_load_dwordx4 v[184:187], v[190:191], off offset:16
	v_lshl_add_u64 v[196:197], v[188:189], 0, v[38:39]
	global_load_dwordx4 v[188:191], v[196:197], off
	global_load_dwordx4 v[192:195], v[196:197], off offset:16
; __device__ __forceinline__ float bf_lo(unsigned u) { return __uint_as_float(u << 16); }
; __device__ __forceinline__ float bf_hi(unsigned u) { return __uint_as_float(u & 0xffff0000u); }
; __device__ __forceinline__ void phase_final(const Params& p) {
;     ...
;     for (int row = blockIdx.x * 8 + wid; row < MT; row += gridDim.x * 8) {
;         const bf16_t* yr = p.QG + (size_t)row * DM; float* xr = p.out + (size_t)row * DM; const float* xi = xrow(p, row);
;         u32x4 v[4]; f32x4 y0[4], y1[4]; float ss = 0.f;
; #pragma unroll
;         for (int i = 0; i < 4; ++i) { const int c = i * 512 + lane * 8; v[i] = *(const u32x4*)(yr + c); y0[i] = *(const f32x4*)(xi + c); y1[i] = *(const f32x4*)(xi + c + 4); }
; #pragma unroll
;         for (int i = 0; i < 4; ++i) {
;             y0[i] += (f32x4){bf_lo(v[i].x), bf_hi(v[i].x), bf_lo(v[i].y), bf_hi(v[i].y)}; y1[i] += (f32x4){bf_lo(v[i].z), bf_hi(v[i].z), bf_lo(v[i].w), bf_hi(v[i].w)};
;             ss += y0[i][0] * y0[i][0] + y0[i][1] * y0[i][1] + y0[i][2] * y0[i][2] + y0[i][3] * y0[i][3] + y1[i][0] * y1[i][0] + y1[i][1] * y1[i][1] + y1[i][2] * y1[i][2] + y1[i][3] * y1[i][3]; }
;         ss = wave_sum(ss);
;         const float rs = rsqrtf(ss * (1.0f / DM) + 1e-6f);
; #pragma unroll
;         for (int i = 0; i < 4; ++i) { const int c = i * 512 + lane * 8;
;             *(f32x4*)(xr + c) = y0[i] * rs * fg0[i]; *(f32x4*)(xr + c + 4) = y1[i] * rs * fg1[i]; }
;     }
.Lfin1_loop:
	s_waitcnt vmcnt(23)
	v_lshlrev_b32_e32 v96, 16, v48
	v_and_b32_e32 v97, 0xffff0000, v48
	v_lshlrev_b32_e32 v48, 16, v49
	v_and_b32_e32 v49, 0xffff0000, v49
	v_lshlrev_b32_e32 v98, 16, v50
	v_and_b32_e32 v99, 0xffff0000, v50
	v_lshlrev_b32_e32 v50, 16, v51
	v_and_b32_e32 v51, 0xffff0000, v51
	s_waitcnt vmcnt(22)
	v_lshlrev_b32_e32 v100, 16, v52
	v_and_b32_e32 v101, 0xffff0000, v52
	v_lshlrev_b32_e32 v102, 16, v54
	v_and_b32_e32 v103, 0xffff0000, v54
	v_lshlrev_b32_e32 v54, 16, v55
	v_and_b32_e32 v55, 0xffff0000, v55
	s_waitcnt vmcnt(19)
	v_pk_add_f32 v[48:49], v[66:67], v[48:49]
	v_pk_add_f32 v[64:65], v[64:65], v[96:97]
	s_waitcnt vmcnt(18)
	v_pk_add_f32 v[66:67], v[70:71], v[50:51]
	s_waitcnt vmcnt(17)
	v_pk_add_f32 v[70:71], v[72:73], v[100:101]
	v_lshlrev_b32_e32 v52, 16, v53
	v_and_b32_e32 v53, 0xffff0000, v53
	s_waitcnt vmcnt(16)
	v_pk_add_f32 v[54:55], v[78:79], v[54:55]
	v_mov_b32_e32 v78, v65
	v_mov_b32_e32 v79, v71
	v_lshlrev_b32_e32 v104, 16, v56
	v_and_b32_e32 v105, 0xffff0000, v56
	v_pk_add_f32 v[52:53], v[74:75], v[52:53]
	v_mov_b32_e32 v50, v64
	v_mov_b32_e32 v51, v70
	v_pk_mul_f32 v[78:79], v[78:79], v[78:79]
	v_lshlrev_b32_e32 v56, 16, v57
	v_and_b32_e32 v57, 0xffff0000, v57
	s_waitcnt vmcnt(15)
	v_pk_add_f32 v[74:75], v[80:81], v[104:105]
	v_mov_b32_e32 v80, v48
	v_mov_b32_e32 v81, v52
	v_pk_fma_f32 v[50:51], v[50:51], v[50:51], v[78:79]
	v_lshlrev_b32_e32 v106, 16, v58
	v_and_b32_e32 v107, 0xffff0000, v58
	v_lshlrev_b32_e32 v108, 16, v60
	v_and_b32_e32 v109, 0xffff0000, v60
	v_pk_add_f32 v[68:69], v[68:69], v[98:99]
	v_pk_add_f32 v[72:73], v[76:77], v[102:103]
	v_pk_add_f32 v[56:57], v[82:83], v[56:57]
	v_mov_b32_e32 v82, v49
	v_mov_b32_e32 v83, v53
	v_pk_fma_f32 v[50:51], v[80:81], v[80:81], v[50:51]
	s_waitcnt vmcnt(14)
	v_pk_add_f32 v[76:77], v[84:85], v[106:107]
	v_mov_b32_e32 v84, v68
	v_mov_b32_e32 v85, v72
	v_pk_fma_f32 v[50:51], v[82:83], v[82:83], v[50:51]
	s_waitcnt vmcnt(13)
	v_pk_add_f32 v[78:79], v[88:89], v[108:109]
	v_lshlrev_b32_e32 v60, 16, v61
	v_pk_fma_f32 v[50:51], v[84:85], v[84:85], v[50:51]
	v_and_b32_e32 v61, 0xffff0000, v61
	v_mov_b32_e32 v84, v75
	v_mov_b32_e32 v85, v79
	v_pk_add_f32 v[60:61], v[90:91], v[60:61]
	v_mov_b32_e32 v82, v74
	v_mov_b32_e32 v83, v78
	v_pk_mul_f32 v[84:85], v[84:85], v[84:85]
	v_lshlrev_b32_e32 v80, 16, v62
	v_and_b32_e32 v81, 0xffff0000, v62
	v_pk_fma_f32 v[82:83], v[82:83], v[82:83], v[84:85]
	v_mov_b32_e32 v84, v56
	v_mov_b32_e32 v85, v60
	v_lshlrev_b32_e32 v58, 16, v59
	v_and_b32_e32 v59, 0xffff0000, v59
	s_waitcnt vmcnt(12)
	v_pk_add_f32 v[80:81], v[92:93], v[80:81]
	v_pk_fma_f32 v[82:83], v[84:85], v[84:85], v[82:83]
	v_mov_b32_e32 v84, v57
	v_mov_b32_e32 v85, v61
	v_pk_add_f32 v[58:59], v[86:87], v[58:59]
	v_mov_b32_e32 v86, v69
	v_mov_b32_e32 v87, v73
	v_lshlrev_b32_e32 v62, 16, v63
	v_and_b32_e32 v63, 0xffff0000, v63
	v_pk_fma_f32 v[82:83], v[84:85], v[84:85], v[82:83]
	v_mov_b32_e32 v84, v76
	v_mov_b32_e32 v85, v80
	v_mov_b32_e32 v96, v66
	v_mov_b32_e32 v97, v54
	v_pk_fma_f32 v[50:51], v[86:87], v[86:87], v[50:51]
	v_pk_add_f32 v[62:63], v[94:95], v[62:63]
	v_pk_fma_f32 v[82:83], v[84:85], v[84:85], v[82:83]
	v_mov_b32_e32 v84, v77
	v_mov_b32_e32 v85, v81
	v_mov_b32_e32 v98, v67
	v_mov_b32_e32 v99, v55
	v_pk_fma_f32 v[50:51], v[96:97], v[96:97], v[50:51]
	v_pk_fma_f32 v[82:83], v[84:85], v[84:85], v[82:83]
	v_mov_b32_e32 v84, v58
	v_mov_b32_e32 v85, v62
	v_pk_fma_f32 v[50:51], v[98:99], v[98:99], v[50:51]
	v_pk_fma_f32 v[82:83], v[84:85], v[84:85], v[82:83]
	v_mov_b32_e32 v84, v59
	v_mov_b32_e32 v85, v63
	v_pk_fma_f32 v[82:83], v[84:85], v[84:85], v[82:83]
	v_add_f32_e32 v47, v50, v51
	v_add_f32_e32 v47, v47, v82
	v_add_f32_e32 v47, v47, v83
	ds_bpermute_b32 v50, v40, v47
	s_waitcnt lgkmcnt(0)
	v_add_f32_e32 v47, v47, v50
	ds_bpermute_b32 v50, v41, v47
	s_waitcnt lgkmcnt(0)
	v_add_f32_e32 v47, v47, v50
	ds_bpermute_b32 v50, v42, v47
	s_waitcnt lgkmcnt(0)
	v_add_f32_e32 v47, v47, v50
	ds_bpermute_b32 v50, v43, v47
	s_waitcnt lgkmcnt(0)
	v_add_f32_e32 v47, v47, v50
	ds_bpermute_b32 v50, v44, v47
	s_waitcnt lgkmcnt(0)
	v_add_f32_e32 v47, v47, v50
	ds_bpermute_b32 v50, v45, v47
	s_waitcnt lgkmcnt(0)
	v_add_f32_e32 v47, v47, v50
	v_fmamk_f32 v47, v47, 0x3a000000, v46
	v_mul_f32_e32 v50, 0x4b800000, v47
	v_cmp_gt_f32_e32 vcc, s4, v47
	s_nop 1
	v_cndmask_b32_e32 v47, v47, v50, vcc
	v_rsq_f32_e32 v47, v47
	v_lshlrev_b64 v[50:51], 13, v[110:111]
	v_lshl_add_u64 v[82:83], s[6:7], 0, v[50:51]
	v_mul_f32_e32 v50, 0x45800000, v47
	v_cndmask_b32_e32 v84, v47, v50, vcc
	v_pk_mul_f32 v[64:65], v[64:65], v[84:85] op_sel_hi:[1,0]
	v_pk_mul_f32 v[48:49], v[48:49], v[84:85] op_sel_hi:[1,0]
	v_pk_mul_f32 v[50:51], v[6:7], v[48:49]
	v_pk_mul_f32 v[48:49], v[4:5], v[64:65]
	v_lshl_add_u64 v[64:65], v[82:83], 0, v[32:33]
	global_store_dwordx4 v[64:65], v[48:51], off
	s_nop 0
	s_nop 0
	v_pk_mul_f32 v[48:49], v[68:69], v[84:85] op_sel_hi:[1,0]
	v_pk_mul_f32 v[50:51], v[66:67], v[84:85] op_sel_hi:[1,0]
	v_pk_mul_f32 v[48:49], v[0:1], v[48:49]
	v_pk_mul_f32 v[50:51], v[2:3], v[50:51]
	global_store_dwordx4 v[64:65], v[48:51], off offset:16
	s_nop 1
	v_pk_mul_f32 v[48:49], v[70:71], v[84:85] op_sel_hi:[1,0]
	v_pk_mul_f32 v[50:51], v[52:53], v[84:85] op_sel_hi:[1,0]
	v_pk_mul_f32 v[48:49], v[12:13], v[48:49]
	v_pk_mul_f32 v[50:51], v[14:15], v[50:51]
	global_store_dwordx4 v[64:65], v[48:51], off offset:2048
	v_lshl_add_u64 v[52:53], v[82:83], 0, v[36:37]
	s_nop 0
	v_pk_mul_f32 v[48:49], v[72:73], v[84:85] op_sel_hi:[1,0]
	v_pk_mul_f32 v[50:51], v[54:55], v[84:85] op_sel_hi:[1,0]
	v_pk_mul_f32 v[48:49], v[8:9], v[48:49]
	v_pk_mul_f32 v[50:51], v[10:11], v[50:51]
	global_store_dwordx4 v[64:65], v[48:51], off offset:2064
	s_nop 1
	v_pk_mul_f32 v[48:49], v[74:75], v[84:85] op_sel_hi:[1,0]
	v_pk_mul_f32 v[50:51], v[56:57], v[84:85] op_sel_hi:[1,0]
	v_pk_mul_f32 v[48:49], v[20:21], v[48:49]
	v_pk_mul_f32 v[50:51], v[22:23], v[50:51]
	global_store_dwordx4 v[52:53], v[48:51], off
	s_nop 1
	v_pk_mul_f32 v[48:49], v[76:77], v[84:85] op_sel_hi:[1,0]
	v_pk_mul_f32 v[50:51], v[58:59], v[84:85] op_sel_hi:[1,0]
	v_pk_mul_f32 v[48:49], v[16:17], v[48:49]
	v_pk_mul_f32 v[50:51], v[18:19], v[50:51]
	global_store_dwordx4 v[52:53], v[48:51], off offset:16
	v_lshl_add_u64 v[52:53], v[82:83], 0, v[38:39]
	s_nop 0
	v_pk_mul_f32 v[48:49], v[78:79], v[84:85] op_sel_hi:[1,0]
	v_pk_mul_f32 v[50:51], v[60:61], v[84:85] op_sel_hi:[1,0]
	v_pk_mul_f32 v[48:49], v[28:29], v[48:49]
	v_pk_mul_f32 v[50:51], v[30:31], v[50:51]
	global_store_dwordx4 v[52:53], v[48:51], off
	s_nop 1
	v_pk_mul_f32 v[48:49], v[80:81], v[84:85] op_sel_hi:[1,0]
	v_pk_mul_f32 v[50:51], v[62:63], v[84:85] op_sel_hi:[1,0]
	v_pk_mul_f32 v[48:49], v[24:25], v[48:49]
	v_pk_mul_f32 v[50:51], v[26:27], v[50:51]
	global_store_dwordx4 v[52:53], v[48:51], off offset:16
	s_addk_i32 s44, 0xc00
	s_cmpk_lt_u32 s44, 0x3000
	s_cbranch_scc0 .Lfin1_noa
; __device__ __forceinline__ void phase_final(const Params& p) {
;     ...
;     for (int row = blockIdx.x * 8 + wid; row < MT; row += gridDim.x * 8) {
;         const bf16_t* yr = p.QG + (size_t)row * DM; float* xr = p.out + (size_t)row * DM; const float* xi = xrow(p, row);
;         u32x4 v[4]; f32x4 y0[4], y1[4]; float ss = 0.f;
; #pragma unroll
;         for (int i = 0; i < 4; ++i) { const int c = i * 512 + lane * 8; v[i] = *(const u32x4*)(yr + c); y0[i] = *(const f32x4*)(xi + c); y1[i] = *(const f32x4*)(xi + c + 4); }
	s_lshr_b32 s46, s44, 11
	s_max_u32 s46, s46, 1
	s_add_i32 s46, s46, -1
	s_lshl_b32 s46, s46, 11
	s_add_i32 s46, s46, s44
	v_mov_b32_e32 v110, s46
	v_ashrrev_i32_e32 v111, 31, v110
	v_add_u32_e32 v100, 0xffff8000, v110
	v_cmp_gt_i32_e32 vcc, s3, v110
	v_lshlrev_b64 v[48:49], 12, v[110:111]
	v_mov_b32_e32 v101, s11
	v_mov_b32_e32 v47, s9
	v_mov_b32_e32 v64, s10
	v_mov_b32_e32 v66, s8
	v_cndmask_b32_e32 v63, 0, v111, vcc
	v_cndmask_b32_e32 v62, v100, v110, vcc
	v_lshl_add_u64 v[60:61], v[34:35], 0, v[48:49]
	v_cndmask_b32_e32 v65, v101, v47, vcc
	v_cndmask_b32_e32 v64, v64, v66, vcc
	v_lshlrev_b64 v[66:67], 13, v[62:63]
	global_load_dwordx4 v[48:51], v[60:61], off
	global_load_dwordx4 v[52:55], v[60:61], off offset:1024
	v_lshl_add_u64 v[88:89], v[64:65], 0, v[66:67]
	v_lshl_add_u64 v[80:81], v[88:89], 0, v[32:33]
	global_load_dwordx4 v[56:59], v[60:61], off offset:2048
	global_load_dwordx4 v[60:63], v[60:61], off offset:3072
	s_nop 0
	global_load_dwordx4 v[64:67], v[80:81], off
	global_load_dwordx4 v[68:71], v[80:81], off offset:16
	global_load_dwordx4 v[72:75], v[80:81], off offset:2048
	global_load_dwordx4 v[76:79], v[80:81], off offset:2064
	v_lshl_add_u64 v[90:91], v[88:89], 0, v[36:37]
	global_load_dwordx4 v[80:83], v[90:91], off
	global_load_dwordx4 v[84:87], v[90:91], off offset:16
	v_lshl_add_u64 v[96:97], v[88:89], 0, v[38:39]
	global_load_dwordx4 v[88:91], v[96:97], off
	global_load_dwordx4 v[92:95], v[96:97], off offset:16
	s_branch .Lfin1_b

; __device__ __forceinline__ float bf_lo(unsigned u) { return __uint_as_float(u << 16); }
; __device__ __forceinline__ float bf_hi(unsigned u) { return __uint_as_float(u & 0xffff0000u); }
; __device__ __forceinline__ void phase_final(const Params& p) {
;     ...
;         for (int i = 0; i < 4; ++i) { const int c = i * 512 + lane * 8; v[i] = *(const u32x4*)(yr + c); y0[i] = *(const f32x4*)(xi + c); y1[i] = *(const f32x4*)(xi + c + 4); }
; #pragma unroll
;         for (int i = 0; i < 4; ++i) {
;             y0[i] += (f32x4){bf_lo(v[i].x), bf_hi(v[i].x), bf_lo(v[i].y), bf_hi(v[i].y)}; y1[i] += (f32x4){bf_lo(v[i].z), bf_hi(v[i].z), bf_lo(v[i].w), bf_hi(v[i].w)};
;             ss += y0[i][0] * y0[i][0] + y0[i][1] * y0[i][1] + y0[i][2] * y0[i][2] + y0[i][3] * y0[i][3] + y1[i][0] * y1[i][0] + y1[i][1] * y1[i][1] + y1[i][2] * y1[i][2] + y1[i][3] * y1[i][3]; }
;         ss = wave_sum(ss);
.Lfin1_b:
	s_cmpk_lt_u32 s45, 0x3000
	s_cbranch_scc0 .Lfin1_done
	s_waitcnt vmcnt(31)
	v_lshlrev_b32_e32 v196, 16, v148
	v_and_b32_e32 v197, 0xffff0000, v148
	v_lshlrev_b32_e32 v148, 16, v149
	v_and_b32_e32 v149, 0xffff0000, v149
	v_lshlrev_b32_e32 v198, 16, v150
	v_and_b32_e32 v199, 0xffff0000, v150
	v_lshlrev_b32_e32 v150, 16, v151
	v_and_b32_e32 v151, 0xffff0000, v151
	s_waitcnt vmcnt(30)
	v_lshlrev_b32_e32 v200, 16, v152
	v_and_b32_e32 v201, 0xffff0000, v152
	v_lshlrev_b32_e32 v202, 16, v154
	v_and_b32_e32 v203, 0xffff0000, v154
	v_lshlrev_b32_e32 v154, 16, v155
	v_and_b32_e32 v155, 0xffff0000, v155
	s_waitcnt vmcnt(27)
	v_pk_add_f32 v[148:149], v[166:167], v[148:149]
	v_pk_add_f32 v[164:165], v[164:165], v[196:197]
	s_waitcnt vmcnt(26)
	v_pk_add_f32 v[166:167], v[170:171], v[150:151]
	s_waitcnt vmcnt(25)
	v_pk_add_f32 v[170:171], v[172:173], v[200:201]
	v_lshlrev_b32_e32 v152, 16, v153
	v_and_b32_e32 v153, 0xffff0000, v153
	s_waitcnt vmcnt(24)
	v_pk_add_f32 v[154:155], v[178:179], v[154:155]
	v_mov_b32_e32 v178, v165
	v_mov_b32_e32 v179, v171
	v_lshlrev_b32_e32 v204, 16, v156
	v_and_b32_e32 v205, 0xffff0000, v156
	v_pk_add_f32 v[152:153], v[174:175], v[152:153]
	v_mov_b32_e32 v150, v164
	v_mov_b32_e32 v151, v170
	v_pk_mul_f32 v[178:179], v[178:179], v[178:179]
	v_lshlrev_b32_e32 v156, 16, v157
	v_and_b32_e32 v157, 0xffff0000, v157
	s_waitcnt vmcnt(23)
	v_pk_add_f32 v[174:175], v[180:181], v[204:205]
	v_mov_b32_e32 v180, v148
	v_mov_b32_e32 v181, v152
	v_pk_fma_f32 v[150:151], v[150:151], v[150:151], v[178:179]
	v_lshlrev_b32_e32 v206, 16, v158
	v_and_b32_e32 v207, 0xffff0000, v158
	v_lshlrev_b32_e32 v208, 16, v160
	v_and_b32_e32 v209, 0xffff0000, v160
	v_pk_add_f32 v[168:169], v[168:169], v[198:199]
	v_pk_add_f32 v[172:173], v[176:177], v[202:203]
	v_pk_add_f32 v[156:157], v[182:183], v[156:157]
	v_mov_b32_e32 v182, v149
	v_mov_b32_e32 v183, v153
	v_pk_fma_f32 v[150:151], v[180:181], v[180:181], v[150:151]
	s_waitcnt vmcnt(22)
	v_pk_add_f32 v[176:177], v[184:185], v[206:207]
	v_mov_b32_e32 v184, v168
	v_mov_b32_e32 v185, v172
	v_pk_fma_f32 v[150:151], v[182:183], v[182:183], v[150:151]
	s_waitcnt vmcnt(21)
	v_pk_add_f32 v[178:179], v[188:189], v[208:209]
	v_lshlrev_b32_e32 v160, 16, v161
	v_pk_fma_f32 v[150:151], v[184:185], v[184:185], v[150:151]
	v_and_b32_e32 v161, 0xffff0000, v161
	v_mov_b32_e32 v184, v175
	v_mov_b32_e32 v185, v179
	v_pk_add_f32 v[160:161], v[190:191], v[160:161]
	v_mov_b32_e32 v182, v174
	v_mov_b32_e32 v183, v178
	v_pk_mul_f32 v[184:185], v[184:185], v[184:185]
	v_lshlrev_b32_e32 v180, 16, v162
	v_and_b32_e32 v181, 0xffff0000, v162
	v_pk_fma_f32 v[182:183], v[182:183], v[182:183], v[184:185]
	v_mov_b32_e32 v184, v156
	v_mov_b32_e32 v185, v160
	v_lshlrev_b32_e32 v158, 16, v159
	v_and_b32_e32 v159, 0xffff0000, v159
	s_waitcnt vmcnt(20)
	v_pk_add_f32 v[180:181], v[192:193], v[180:181]
	v_pk_fma_f32 v[182:183], v[184:185], v[184:185], v[182:183]
	v_mov_b32_e32 v184, v157
	v_mov_b32_e32 v185, v161
	v_pk_add_f32 v[158:159], v[186:187], v[158:159]
	v_mov_b32_e32 v186, v169
	v_mov_b32_e32 v187, v173
	v_lshlrev_b32_e32 v162, 16, v163
	v_and_b32_e32 v163, 0xffff0000, v163
	v_pk_fma_f32 v[182:183], v[184:185], v[184:185], v[182:183]
	v_mov_b32_e32 v184, v176
	v_mov_b32_e32 v185, v180
	v_mov_b32_e32 v196, v166
	v_mov_b32_e32 v197, v154
	v_pk_fma_f32 v[150:151], v[186:187], v[186:187], v[150:151]
	v_pk_add_f32 v[162:163], v[194:195], v[162:163]
	v_pk_fma_f32 v[182:183], v[184:185], v[184:185], v[182:183]
	v_mov_b32_e32 v184, v177
	v_mov_b32_e32 v185, v181
	v_mov_b32_e32 v198, v167
	v_mov_b32_e32 v199, v155
	v_pk_fma_f32 v[150:151], v[196:197], v[196:197], v[150:151]
	v_pk_fma_f32 v[182:183], v[184:185], v[184:185], v[182:183]
	v_mov_b32_e32 v184, v158
	v_mov_b32_e32 v185, v162
	v_pk_fma_f32 v[150:151], v[198:199], v[198:199], v[150:151]
	v_pk_fma_f32 v[182:183], v[184:185], v[184:185], v[182:183]
	v_mov_b32_e32 v184, v159
	v_mov_b32_e32 v185, v163
	v_pk_fma_f32 v[182:183], v[184:185], v[184:185], v[182:183]
	v_add_f32_e32 v147, v150, v151
	v_add_f32_e32 v147, v147, v182
	v_add_f32_e32 v147, v147, v183
	ds_bpermute_b32 v150, v40, v147
	s_waitcnt lgkmcnt(0)
	v_add_f32_e32 v147, v147, v150
	ds_bpermute_b32 v150, v41, v147
	s_waitcnt lgkmcnt(0)
	v_add_f32_e32 v147, v147, v150
	ds_bpermute_b32 v150, v42, v147
	s_waitcnt lgkmcnt(0)
	v_add_f32_e32 v147, v147, v150
	ds_bpermute_b32 v150, v43, v147
	s_waitcnt lgkmcnt(0)
	v_add_f32_e32 v147, v147, v150
	ds_bpermute_b32 v150, v44, v147
	s_waitcnt lgkmcnt(0)
; __device__ __forceinline__ void phase_final(const Params& p) {
;     ...
;             ss += y0[i][0] * y0[i][0] + y0[i][1] * y0[i][1] + y0[i][2] * y0[i][2] + y0[i][3] * y0[i][3] + y1[i][0] * y1[i][0] + y1[i][1] * y1[i][1] + y1[i][2] * y1[i][2] + y1[i][3] * y1[i][3]; }
;         ss = wave_sum(ss);
;         const float rs = rsqrtf(ss * (1.0f / DM) + 1e-6f);
; #pragma unroll
;         for (int i = 0; i < 4; ++i) { const int c = i * 512 + lane * 8;
;             *(f32x4*)(xr + c) = y0[i] * rs * fg0[i]; *(f32x4*)(xr + c + 4) = y1[i] * rs * fg1[i]; }
;     }
	v_add_f32_e32 v147, v147, v150
	ds_bpermute_b32 v150, v45, v147
	s_waitcnt lgkmcnt(0)
	v_add_f32_e32 v147, v147, v150
	v_fmamk_f32 v147, v147, 0x3a000000, v46
	v_mul_f32_e32 v150, 0x4b800000, v147
	v_cmp_gt_f32_e32 vcc, s4, v147
	s_nop 1
	v_cndmask_b32_e32 v147, v147, v150, vcc
	v_rsq_f32_e32 v147, v147
	v_lshlrev_b64 v[150:151], 13, v[210:211]
	v_lshl_add_u64 v[182:183], s[6:7], 0, v[150:151]
	v_mul_f32_e32 v150, 0x45800000, v147
	v_cndmask_b32_e32 v184, v147, v150, vcc
	v_pk_mul_f32 v[164:165], v[164:165], v[184:185] op_sel_hi:[1,0]
	v_pk_mul_f32 v[148:149], v[148:149], v[184:185] op_sel_hi:[1,0]
	v_pk_mul_f32 v[150:151], v[6:7], v[148:149]
	v_pk_mul_f32 v[148:149], v[4:5], v[164:165]
	v_lshl_add_u64 v[164:165], v[182:183], 0, v[32:33]
	global_store_dwordx4 v[164:165], v[148:151], off
	s_nop 0
	s_nop 0
	v_pk_mul_f32 v[148:149], v[168:169], v[184:185] op_sel_hi:[1,0]
	v_pk_mul_f32 v[150:151], v[166:167], v[184:185] op_sel_hi:[1,0]
	v_pk_mul_f32 v[148:149], v[0:1], v[148:149]
	v_pk_mul_f32 v[150:151], v[2:3], v[150:151]
	global_store_dwordx4 v[164:165], v[148:151], off offset:16
	s_nop 1
	v_pk_mul_f32 v[148:149], v[170:171], v[184:185] op_sel_hi:[1,0]
	v_pk_mul_f32 v[150:151], v[152:153], v[184:185] op_sel_hi:[1,0]
	v_pk_mul_f32 v[148:149], v[12:13], v[148:149]
	v_pk_mul_f32 v[150:151], v[14:15], v[150:151]
	global_store_dwordx4 v[164:165], v[148:151], off offset:2048
	v_lshl_add_u64 v[152:153], v[182:183], 0, v[36:37]
	s_nop 0
	v_pk_mul_f32 v[148:149], v[172:173], v[184:185] op_sel_hi:[1,0]
	v_pk_mul_f32 v[150:151], v[154:155], v[184:185] op_sel_hi:[1,0]
	v_pk_mul_f32 v[148:149], v[8:9], v[148:149]
	v_pk_mul_f32 v[150:151], v[10:11], v[150:151]
	global_store_dwordx4 v[164:165], v[148:151], off offset:2064
	s_nop 1
	v_pk_mul_f32 v[148:149], v[174:175], v[184:185] op_sel_hi:[1,0]
	v_pk_mul_f32 v[150:151], v[156:157], v[184:185] op_sel_hi:[1,0]
	v_pk_mul_f32 v[148:149], v[20:21], v[148:149]
	v_pk_mul_f32 v[150:151], v[22:23], v[150:151]
	global_store_dwordx4 v[152:153], v[148:151], off
	s_nop 1
	v_pk_mul_f32 v[148:149], v[176:177], v[184:185] op_sel_hi:[1,0]
	v_pk_mul_f32 v[150:151], v[158:159], v[184:185] op_sel_hi:[1,0]
	v_pk_mul_f32 v[148:149], v[16:17], v[148:149]
	v_pk_mul_f32 v[150:151], v[18:19], v[150:151]
	global_store_dwordx4 v[152:153], v[148:151], off offset:16
	v_lshl_add_u64 v[152:153], v[182:183], 0, v[38:39]
	s_nop 0
	v_pk_mul_f32 v[148:149], v[178:179], v[184:185] op_sel_hi:[1,0]
	v_pk_mul_f32 v[150:151], v[160:161], v[184:185] op_sel_hi:[1,0]
	v_pk_mul_f32 v[148:149], v[28:29], v[148:149]
	v_pk_mul_f32 v[150:151], v[30:31], v[150:151]
	global_store_dwordx4 v[152:153], v[148:151], off
	s_nop 1
	v_pk_mul_f32 v[148:149], v[180:181], v[184:185] op_sel_hi:[1,0]
	v_pk_mul_f32 v[150:151], v[162:163], v[184:185] op_sel_hi:[1,0]
	v_pk_mul_f32 v[148:149], v[24:25], v[148:149]
	v_pk_mul_f32 v[150:151], v[26:27], v[150:151]
	global_store_dwordx4 v[152:153], v[148:151], off offset:16
	s_addk_i32 s45, 0xc00
	s_cmpk_lt_u32 s45, 0x3000
	s_cbranch_scc0 .Lfin1_nob
	s_lshr_b32 s46, s45, 11
	s_max_u32 s46, s46, 1
	s_add_i32 s46, s46, -1
	s_lshl_b32 s46, s46, 11
	s_add_i32 s46, s46, s45
	v_mov_b32_e32 v210, s46
	v_ashrrev_i32_e32 v211, 31, v210
	v_add_u32_e32 v200, 0xffff8000, v210
	v_cmp_gt_i32_e32 vcc, s3, v210
	v_lshlrev_b64 v[148:149], 12, v[210:211]
	v_mov_b32_e32 v201, s11
	v_mov_b32_e32 v147, s9
	v_mov_b32_e32 v164, s10
	v_mov_b32_e32 v166, s8
	v_cndmask_b32_e32 v163, 0, v211, vcc
	v_cndmask_b32_e32 v162, v200, v210, vcc
	v_lshl_add_u64 v[160:161], v[34:35], 0, v[148:149]
	v_cndmask_b32_e32 v165, v201, v147, vcc
	v_cndmask_b32_e32 v164, v164, v166, vcc
	v_lshlrev_b64 v[166:167], 13, v[162:163]
	global_load_dwordx4 v[148:151], v[160:161], off
	global_load_dwordx4 v[152:155], v[160:161], off offset:1024
	v_lshl_add_u64 v[188:189], v[164:165], 0, v[166:167]
	v_lshl_add_u64 v[180:181], v[188:189], 0, v[32:33]
	global_load_dwordx4 v[156:159], v[160:161], off offset:2048
	global_load_dwordx4 v[160:163], v[160:161], off offset:3072
	s_nop 0
	global_load_dwordx4 v[164:167], v[180:181], off
	global_load_dwordx4 v[168:171], v[180:181], off offset:16
	global_load_dwordx4 v[172:175], v[180:181], off offset:2048
	global_load_dwordx4 v[176:179], v[180:181], off offset:2064
	v_lshl_add_u64 v[190:191], v[188:189], 0, v[36:37]
	global_load_dwordx4 v[180:183], v[190:191], off
	global_load_dwordx4 v[184:187], v[190:191], off offset:16
	v_lshl_add_u64 v[196:197], v[188:189], 0, v[38:39]
	global_load_dwordx4 v[188:191], v[196:197], off
	global_load_dwordx4 v[192:195], v[196:197], off offset:16
	s_branch .Lfin1_c

; __device__ __forceinline__ unsigned xb_ld(unsigned* p)              { return __hip_atomic_load(p, __ATOMIC_RELAXED, __HIP_MEMORY_SCOPE_AGENT); }
; __device__ __forceinline__ void xcd_barrier_complete(unsigned* bar, unsigned x, unsigned& nloc, unsigned& nx) {
;     ...
;         for (unsigned j = 0; j < 16; ++j) { const unsigned c = xb_ld(&bar[XB_XCNT(j)]); sum += c; cnt += (c > 0u) ? 1u : 0u; mine = (j == x) ? c : mine; }
;         if (sum == G) break;
;         __builtin_amdgcn_s_sleep(1);
;         if ((++sp & 255u) == 0u) { if (xb_ld(&bar[XB_TMO])) break; if (sp > XB_SPIN_CAP) { atomicAdd(&bar[XB_TMO], 1u); break; } }
;     }
;     nloc = mine > 0u ? mine : 1u; nx = cnt > 0u ? cnt : 1u;
.Lfin1_c:
	s_cmpk_lt_u32 s44, 0x3000
	s_cbranch_scc1 .Lfin1_loop
.Lfin1_done:
.LBB0_564:
	s_waitcnt vmcnt(0)
	s_waitcnt vmcnt(0) lgkmcnt(0)
	s_barrier
	s_mov_b64 s[2:3], exec
	v_readlane_b32 s4, v244, 1
	v_readlane_b32 s5, v244, 2
	s_and_b64 s[4:5], s[2:3], s[4:5]
	s_mov_b64 exec, s[4:5]
	s_cbranch_execz .LBB0_616
	v_cmp_eq_u32_e32 vcc, 0, v130
	s_waitcnt vmcnt(0) expcnt(0) lgkmcnt(0)
	s_and_saveexec_b64 s[4:5], vcc
	s_cbranch_execz .LBB0_580
	v_readlane_b32 s6, v244, 0
	s_mul_i32 s20, s39, s6
	s_add_u32 s6, s36, 0x1000
	s_addc_u32 s7, s37, 0
	s_add_u32 s8, s36, 0x1100
	s_addc_u32 s9, s37, 0
	s_add_u32 s10, s36, 0x1200
	s_addc_u32 s11, s37, 0
	s_add_u32 s12, s36, 0x1300
	s_mul_i32 s20, s20, s38
	s_addc_u32 s13, s37, 0
	s_mov_b32 s21, 1
	v_mov_b32_e32 v16, 0
	s_branch .LBB0_568

; __device__ __forceinline__ void phase_final(const Params& p) {
;     const int tid = threadIdx.x, lane = tid & 63, wid = tid >> 6;
;     f32x4 fg0[4], fg1[4];
; #pragma unroll
;     for (int i = 0; i < 4; ++i) { const int c = i * 512 + lane * 8; fg0[i] = *(const f32x4*)(p.final_g + c); fg1[i] = *(const f32x4*)(p.final_g + c + 4); }
;     for (int row = blockIdx.x * 8 + wid; row < MT; row += gridDim.x * 8) {
;         const bf16_t* yr = p.QG + (size_t)row * DM; float* xr = p.out + (size_t)row * DM; const float* xi = xrow(p, row);
;         u32x4 v[4]; f32x4 y0[4], y1[4]; float ss = 0.f;
; #pragma unroll
;         for (int i = 0; i < 4; ++i) { const int c = i * 512 + lane * 8; v[i] = *(const u32x4*)(yr + c); y0[i] = *(const f32x4*)(xi + c); y1[i] = *(const f32x4*)(xi + c + 4); }
.LBB0_616:
	s_or_b64 exec, exec, s[2:3]
	v_readlane_b32 s4, v244, 4
	v_readlane_b32 s5, v244, 5
	s_barrier
	s_and_saveexec_b64 s[2:3], s[4:5]
	s_cbranch_execz .LBB0_619
	s_load_dwordx4 s[4:7], s[0:1], 0xa8
	s_load_dwordx4 s[8:11], s[0:1], 0x0
	v_and_b32_e32 v36, 0x1f8, v131
	v_lshlrev_b32_e32 v16, 2, v36
	v_or_b32_e32 v38, 0x400, v36
	s_waitcnt lgkmcnt(0)
	global_load_dwordx4 v[0:3], v16, s[4:5] offset:16
	global_load_dwordx4 v[4:7], v16, s[4:5]
	global_load_dwordx4 v[8:11], v16, s[4:5] offset:2064
	global_load_dwordx4 v[12:15], v16, s[4:5] offset:2048
	v_or_b32_e32 v46, 0x600, v36
	v_lshlrev_b32_e32 v24, 2, v38
	v_lshlrev_b32_e32 v32, 2, v46
	global_load_dwordx4 v[16:19], v24, s[4:5] offset:16
	global_load_dwordx4 v[20:23], v24, s[4:5]
	s_nop 0
	global_load_dwordx4 v[24:27], v32, s[4:5] offset:16
	global_load_dwordx4 v[28:31], v32, s[4:5]
	v_mbcnt_hi_u32_b32 v32, -1, v129
	v_and_b32_e32 v34, 64, v32
	v_add_u32_e32 v34, 64, v34
	v_xor_b32_e32 v35, 32, v32
	v_cmp_lt_i32_e32 vcc, v35, v34
	s_load_dwordx2 s[48:49], s[0:1], 0xe8
	v_mov_b32_e32 v33, 0
	v_cndmask_b32_e32 v35, v32, v35, vcc
	v_lshlrev_b32_e32 v40, 2, v35
	v_xor_b32_e32 v35, 16, v32
	v_cmp_lt_i32_e32 vcc, v35, v34
	s_mov_b32 s3, 0x8000
	v_cndmask_b32_e32 v35, v32, v35, vcc
	v_lshlrev_b32_e32 v41, 2, v35
	v_xor_b32_e32 v35, 8, v32
	v_cmp_lt_i32_e32 vcc, v35, v34
	s_mov_b32 s4, 0x800000
	s_mov_b32 s5, 0x87ff
	v_cndmask_b32_e32 v35, v32, v35, vcc
	v_lshlrev_b32_e32 v42, 2, v35
	v_xor_b32_e32 v35, 4, v32
	v_cmp_lt_i32_e32 vcc, v35, v34
	s_nop 1
	v_cndmask_b32_e32 v35, v32, v35, vcc
	v_lshlrev_b32_e32 v43, 2, v35
	v_xor_b32_e32 v35, 2, v32
	v_cmp_lt_i32_e32 vcc, v35, v34
	s_nop 1
	v_cndmask_b32_e32 v35, v32, v35, vcc
	v_lshlrev_b32_e32 v44, 2, v35
	v_xor_b32_e32 v35, 1, v32
	v_cmp_lt_i32_e32 vcc, v35, v34
	s_nop 1
	v_cndmask_b32_e32 v32, v32, v35, vcc
	v_lshlrev_b32_e32 v45, 2, v32
	v_lshlrev_b32_e32 v32, 1, v36
	s_waitcnt lgkmcnt(0)
	v_lshl_add_u64 v[34:35], s[48:49], 0, v[32:33]
	v_lshlrev_b32_e32 v32, 2, v36
	v_lshlrev_b32_e32 v36, 2, v38
	v_lshlrev_b32_e32 v38, 2, v46
	v_mov_b32_e32 v46, 0x358637bd
	v_mov_b32_e32 v37, 0
	v_mov_b32_e32 v39, 0
	v_readfirstlane_b32 s44, v128
	s_nop 3
	s_addk_i32 s44, 0x1000
	s_mov_b32 s45, s44
	s_cmpk_lt_u32 s45, 0x5000
	s_cselect_b32 s46, 0x800, 0
	s_addk_i32 s46, 0x800
	s_add_i32 s45, s45, s46
	s_mov_b32 s46, s44
	v_mov_b32_e32 v110, s46
	v_ashrrev_i32_e32 v111, 31, v110
	v_add_u32_e32 v100, 0xffff8000, v110
	v_cmp_gt_i32_e32 vcc, s3, v110
	v_lshlrev_b64 v[48:49], 12, v[110:111]
	v_mov_b32_e32 v101, s11
	v_mov_b32_e32 v47, s9
	v_mov_b32_e32 v64, s10
	v_mov_b32_e32 v66, s8
	v_cndmask_b32_e32 v63, 0, v111, vcc
	v_cndmask_b32_e32 v62, v100, v110, vcc
	v_lshl_add_u64 v[60:61], v[34:35], 0, v[48:49]
	v_cndmask_b32_e32 v65, v101, v47, vcc
	v_cndmask_b32_e32 v64, v64, v66, vcc
	v_lshlrev_b64 v[66:67], 13, v[62:63]
	global_load_dwordx4 v[48:51], v[60:61], off
	global_load_dwordx4 v[52:55], v[60:61], off offset:1024
	v_lshl_add_u64 v[88:89], v[64:65], 0, v[66:67]
	v_lshl_add_u64 v[80:81], v[88:89], 0, v[32:33]
	global_load_dwordx4 v[56:59], v[60:61], off offset:2048
	global_load_dwordx4 v[60:63], v[60:61], off offset:3072
	s_nop 0
	global_load_dwordx4 v[64:67], v[80:81], off
	global_load_dwordx4 v[68:71], v[80:81], off offset:16
	global_load_dwordx4 v[72:75], v[80:81], off offset:2048
	global_load_dwordx4 v[76:79], v[80:81], off offset:2064
	v_lshl_add_u64 v[90:91], v[88:89], 0, v[36:37]
	global_load_dwordx4 v[80:83], v[90:91], off
	global_load_dwordx4 v[84:87], v[90:91], off offset:16
	v_lshl_add_u64 v[96:97], v[88:89], 0, v[38:39]
	global_load_dwordx4 v[88:91], v[96:97], off
	global_load_dwordx4 v[92:95], v[96:97], off offset:16
	s_mov_b32 s46, s45
	v_mov_b32_e32 v210, s46
	v_ashrrev_i32_e32 v211, 31, v210
	v_add_u32_e32 v200, 0xffff8000, v210
	v_cmp_gt_i32_e32 vcc, s3, v210
	v_lshlrev_b64 v[148:149], 12, v[210:211]
	v_mov_b32_e32 v201, s11
	v_mov_b32_e32 v147, s9
	v_mov_b32_e32 v164, s10
	v_mov_b32_e32 v166, s8
	v_cndmask_b32_e32 v163, 0, v211, vcc
	v_cndmask_b32_e32 v162, v200, v210, vcc
	v_lshl_add_u64 v[160:161], v[34:35], 0, v[148:149]
	v_cndmask_b32_e32 v165, v201, v147, vcc
	v_cndmask_b32_e32 v164, v164, v166, vcc
	v_lshlrev_b64 v[166:167], 13, v[162:163]
	global_load_dwordx4 v[148:151], v[160:161], off
	global_load_dwordx4 v[152:155], v[160:161], off offset:1024
	v_lshl_add_u64 v[188:189], v[164:165], 0, v[166:167]
	v_lshl_add_u64 v[180:181], v[188:189], 0, v[32:33]
	global_load_dwordx4 v[156:159], v[160:161], off offset:2048
	global_load_dwordx4 v[160:163], v[160:161], off offset:3072
	s_nop 0
	global_load_dwordx4 v[164:167], v[180:181], off
	global_load_dwordx4 v[168:171], v[180:181], off offset:16
	global_load_dwordx4 v[172:175], v[180:181], off offset:2048
	global_load_dwordx4 v[176:179], v[180:181], off offset:2064
	v_lshl_add_u64 v[190:191], v[188:189], 0, v[36:37]
	global_load_dwordx4 v[180:183], v[190:191], off
	global_load_dwordx4 v[184:187], v[190:191], off offset:16
	v_lshl_add_u64 v[196:197], v[188:189], 0, v[38:39]
	global_load_dwordx4 v[188:191], v[196:197], off
	global_load_dwordx4 v[192:195], v[196:197], off offset:16
; __device__ __forceinline__ float bf_lo(unsigned u) { return __uint_as_float(u << 16); }
; __device__ __forceinline__ float bf_hi(unsigned u) { return __uint_as_float(u & 0xffff0000u); }
; __device__ __forceinline__ void phase_final(const Params& p) {
;     ...
;     for (int row = blockIdx.x * 8 + wid; row < MT; row += gridDim.x * 8) {
;         const bf16_t* yr = p.QG + (size_t)row * DM; float* xr = p.out + (size_t)row * DM; const float* xi = xrow(p, row);
;         u32x4 v[4]; f32x4 y0[4], y1[4]; float ss = 0.f;
; #pragma unroll
;         for (int i = 0; i < 4; ++i) { const int c = i * 512 + lane * 8; v[i] = *(const u32x4*)(yr + c); y0[i] = *(const f32x4*)(xi + c); y1[i] = *(const f32x4*)(xi + c + 4); }
; #pragma unroll
;         for (int i = 0; i < 4; ++i) {
;             y0[i] += (f32x4){bf_lo(v[i].x), bf_hi(v[i].x), bf_lo(v[i].y), bf_hi(v[i].y)}; y1[i] += (f32x4){bf_lo(v[i].z), bf_hi(v[i].z), bf_lo(v[i].w), bf_hi(v[i].w)};
;             ss += y0[i][0] * y0[i][0] + y0[i][1] * y0[i][1] + y0[i][2] * y0[i][2] + y0[i][3] * y0[i][3] + y1[i][0] * y1[i][0] + y1[i][1] * y1[i][1] + y1[i][2] * y1[i][2] + y1[i][3] * y1[i][3]; }
;         ss = wave_sum(ss);
.Lfin2_loop:
	s_waitcnt vmcnt(23)
	v_lshlrev_b32_e32 v96, 16, v48
	v_and_b32_e32 v97, 0xffff0000, v48
	v_lshlrev_b32_e32 v48, 16, v49
	v_and_b32_e32 v49, 0xffff0000, v49
	v_lshlrev_b32_e32 v98, 16, v50
	v_and_b32_e32 v99, 0xffff0000, v50
	v_lshlrev_b32_e32 v50, 16, v51
	v_and_b32_e32 v51, 0xffff0000, v51
	s_waitcnt vmcnt(22)
	v_lshlrev_b32_e32 v100, 16, v52
	v_and_b32_e32 v101, 0xffff0000, v52
	v_lshlrev_b32_e32 v102, 16, v54
	v_and_b32_e32 v103, 0xffff0000, v54
	v_lshlrev_b32_e32 v54, 16, v55
	v_and_b32_e32 v55, 0xffff0000, v55
	s_waitcnt vmcnt(19)
	v_pk_add_f32 v[48:49], v[66:67], v[48:49]
	v_pk_add_f32 v[64:65], v[64:65], v[96:97]
	s_waitcnt vmcnt(18)
	v_pk_add_f32 v[66:67], v[70:71], v[50:51]
	s_waitcnt vmcnt(17)
	v_pk_add_f32 v[70:71], v[72:73], v[100:101]
	v_lshlrev_b32_e32 v52, 16, v53
	v_and_b32_e32 v53, 0xffff0000, v53
	s_waitcnt vmcnt(16)
	v_pk_add_f32 v[54:55], v[78:79], v[54:55]
	v_mov_b32_e32 v78, v65
	v_mov_b32_e32 v79, v71
	v_lshlrev_b32_e32 v104, 16, v56
	v_and_b32_e32 v105, 0xffff0000, v56
	v_pk_add_f32 v[52:53], v[74:75], v[52:53]
	v_mov_b32_e32 v50, v64
	v_mov_b32_e32 v51, v70
	v_pk_mul_f32 v[78:79], v[78:79], v[78:79]
	v_lshlrev_b32_e32 v56, 16, v57
	v_and_b32_e32 v57, 0xffff0000, v57
	s_waitcnt vmcnt(15)
	v_pk_add_f32 v[74:75], v[80:81], v[104:105]
	v_mov_b32_e32 v80, v48
	v_mov_b32_e32 v81, v52
	v_pk_fma_f32 v[50:51], v[50:51], v[50:51], v[78:79]
	v_lshlrev_b32_e32 v106, 16, v58
	v_and_b32_e32 v107, 0xffff0000, v58
	v_lshlrev_b32_e32 v108, 16, v60
	v_and_b32_e32 v109, 0xffff0000, v60
	v_pk_add_f32 v[68:69], v[68:69], v[98:99]
	v_pk_add_f32 v[72:73], v[76:77], v[102:103]
	v_pk_add_f32 v[56:57], v[82:83], v[56:57]
	v_mov_b32_e32 v82, v49
	v_mov_b32_e32 v83, v53
	v_pk_fma_f32 v[50:51], v[80:81], v[80:81], v[50:51]
	s_waitcnt vmcnt(14)
	v_pk_add_f32 v[76:77], v[84:85], v[106:107]
	v_mov_b32_e32 v84, v68
	v_mov_b32_e32 v85, v72
	v_pk_fma_f32 v[50:51], v[82:83], v[82:83], v[50:51]
	s_waitcnt vmcnt(13)
	v_pk_add_f32 v[78:79], v[88:89], v[108:109]
	v_lshlrev_b32_e32 v60, 16, v61
	v_pk_fma_f32 v[50:51], v[84:85], v[84:85], v[50:51]
	v_and_b32_e32 v61, 0xffff0000, v61
	v_mov_b32_e32 v84, v75
	v_mov_b32_e32 v85, v79
	v_pk_add_f32 v[60:61], v[90:91], v[60:61]
	v_mov_b32_e32 v82, v74
	v_mov_b32_e32 v83, v78
	v_pk_mul_f32 v[84:85], v[84:85], v[84:85]
	v_lshlrev_b32_e32 v80, 16, v62
	v_and_b32_e32 v81, 0xffff0000, v62
	v_pk_fma_f32 v[82:83], v[82:83], v[82:83], v[84:85]
	v_mov_b32_e32 v84, v56
	v_mov_b32_e32 v85, v60
	v_lshlrev_b32_e32 v58, 16, v59
	v_and_b32_e32 v59, 0xffff0000, v59
	s_waitcnt vmcnt(12)
	v_pk_add_f32 v[80:81], v[92:93], v[80:81]
	v_pk_fma_f32 v[82:83], v[84:85], v[84:85], v[82:83]
	v_mov_b32_e32 v84, v57
	v_mov_b32_e32 v85, v61
	v_pk_add_f32 v[58:59], v[86:87], v[58:59]
	v_mov_b32_e32 v86, v69
	v_mov_b32_e32 v87, v73
	v_lshlrev_b32_e32 v62, 16, v63
	v_and_b32_e32 v63, 0xffff0000, v63
	v_pk_fma_f32 v[82:83], v[84:85], v[84:85], v[82:83]
	v_mov_b32_e32 v84, v76
	v_mov_b32_e32 v85, v80
	v_mov_b32_e32 v96, v66
	v_mov_b32_e32 v97, v54
	v_pk_fma_f32 v[50:51], v[86:87], v[86:87], v[50:51]
	v_pk_add_f32 v[62:63], v[94:95], v[62:63]
	v_pk_fma_f32 v[82:83], v[84:85], v[84:85], v[82:83]
	v_mov_b32_e32 v84, v77
	v_mov_b32_e32 v85, v81
	v_mov_b32_e32 v98, v67
	v_mov_b32_e32 v99, v55
	v_pk_fma_f32 v[50:51], v[96:97], v[96:97], v[50:51]
	v_pk_fma_f32 v[82:83], v[84:85], v[84:85], v[82:83]
	v_mov_b32_e32 v84, v58
	v_mov_b32_e32 v85, v62
	v_pk_fma_f32 v[50:51], v[98:99], v[98:99], v[50:51]
	v_pk_fma_f32 v[82:83], v[84:85], v[84:85], v[82:83]
	v_mov_b32_e32 v84, v59
	v_mov_b32_e32 v85, v63
	v_pk_fma_f32 v[82:83], v[84:85], v[84:85], v[82:83]
	v_add_f32_e32 v47, v50, v51
	v_add_f32_e32 v47, v47, v82
	v_add_f32_e32 v47, v47, v83
	ds_bpermute_b32 v50, v40, v47
	s_waitcnt lgkmcnt(0)
	v_add_f32_e32 v47, v47, v50
	ds_bpermute_b32 v50, v41, v47
	s_waitcnt lgkmcnt(0)
	v_add_f32_e32 v47, v47, v50
	ds_bpermute_b32 v50, v42, v47
	s_waitcnt lgkmcnt(0)
	v_add_f32_e32 v47, v47, v50
	ds_bpermute_b32 v50, v43, v47
	s_waitcnt lgkmcnt(0)
	v_add_f32_e32 v47, v47, v50
	ds_bpermute_b32 v50, v44, v47
	s_waitcnt lgkmcnt(0)
	v_add_f32_e32 v47, v47, v50
	ds_bpermute_b32 v50, v45, v47
	s_waitcnt lgkmcnt(0)
; __device__ __forceinline__ void phase_final(const Params& p) {
;     ...
;             ss += y0[i][0] * y0[i][0] + y0[i][1] * y0[i][1] + y0[i][2] * y0[i][2] + y0[i][3] * y0[i][3] + y1[i][0] * y1[i][0] + y1[i][1] * y1[i][1] + y1[i][2] * y1[i][2] + y1[i][3] * y1[i][3]; }
;         ss = wave_sum(ss);
;         const float rs = rsqrtf(ss * (1.0f / DM) + 1e-6f);
; #pragma unroll
;         for (int i = 0; i < 4; ++i) { const int c = i * 512 + lane * 8;
;             *(f32x4*)(xr + c) = y0[i] * rs * fg0[i]; *(f32x4*)(xr + c + 4) = y1[i] * rs * fg1[i]; }
;     }
	v_add_f32_e32 v47, v47, v50
	v_fmamk_f32 v47, v47, 0x3a000000, v46
	v_mul_f32_e32 v50, 0x4b800000, v47
	v_cmp_gt_f32_e32 vcc, s4, v47
	s_nop 1
	v_cndmask_b32_e32 v47, v47, v50, vcc
	v_rsq_f32_e32 v47, v47
	v_lshlrev_b64 v[50:51], 13, v[110:111]
	v_lshl_add_u64 v[82:83], s[6:7], 0, v[50:51]
	v_mul_f32_e32 v50, 0x45800000, v47
	v_cndmask_b32_e32 v84, v47, v50, vcc
	v_pk_mul_f32 v[64:65], v[64:65], v[84:85] op_sel_hi:[1,0]
	v_pk_mul_f32 v[48:49], v[48:49], v[84:85] op_sel_hi:[1,0]
	v_pk_mul_f32 v[50:51], v[6:7], v[48:49]
	v_pk_mul_f32 v[48:49], v[4:5], v[64:65]
	v_lshl_add_u64 v[64:65], v[82:83], 0, v[32:33]
	global_store_dwordx4 v[64:65], v[48:51], off
	s_nop 0
	s_nop 0
	v_pk_mul_f32 v[48:49], v[68:69], v[84:85] op_sel_hi:[1,0]
	v_pk_mul_f32 v[50:51], v[66:67], v[84:85] op_sel_hi:[1,0]
	v_pk_mul_f32 v[48:49], v[0:1], v[48:49]
	v_pk_mul_f32 v[50:51], v[2:3], v[50:51]
	global_store_dwordx4 v[64:65], v[48:51], off offset:16
	s_nop 1
	v_pk_mul_f32 v[48:49], v[70:71], v[84:85] op_sel_hi:[1,0]
	v_pk_mul_f32 v[50:51], v[52:53], v[84:85] op_sel_hi:[1,0]
	v_pk_mul_f32 v[48:49], v[12:13], v[48:49]
	v_pk_mul_f32 v[50:51], v[14:15], v[50:51]
	global_store_dwordx4 v[64:65], v[48:51], off offset:2048
	v_lshl_add_u64 v[52:53], v[82:83], 0, v[36:37]
	s_nop 0
	v_pk_mul_f32 v[48:49], v[72:73], v[84:85] op_sel_hi:[1,0]
	v_pk_mul_f32 v[50:51], v[54:55], v[84:85] op_sel_hi:[1,0]
	v_pk_mul_f32 v[48:49], v[8:9], v[48:49]
	v_pk_mul_f32 v[50:51], v[10:11], v[50:51]
	global_store_dwordx4 v[64:65], v[48:51], off offset:2064
	s_nop 1
	v_pk_mul_f32 v[48:49], v[74:75], v[84:85] op_sel_hi:[1,0]
	v_pk_mul_f32 v[50:51], v[56:57], v[84:85] op_sel_hi:[1,0]
	v_pk_mul_f32 v[48:49], v[20:21], v[48:49]
	v_pk_mul_f32 v[50:51], v[22:23], v[50:51]
	global_store_dwordx4 v[52:53], v[48:51], off
	s_nop 1
	v_pk_mul_f32 v[48:49], v[76:77], v[84:85] op_sel_hi:[1,0]
	v_pk_mul_f32 v[50:51], v[58:59], v[84:85] op_sel_hi:[1,0]
	v_pk_mul_f32 v[48:49], v[16:17], v[48:49]
	v_pk_mul_f32 v[50:51], v[18:19], v[50:51]
	global_store_dwordx4 v[52:53], v[48:51], off offset:16
	v_lshl_add_u64 v[52:53], v[82:83], 0, v[38:39]
	s_nop 0
	v_pk_mul_f32 v[48:49], v[78:79], v[84:85] op_sel_hi:[1,0]
	v_pk_mul_f32 v[50:51], v[60:61], v[84:85] op_sel_hi:[1,0]
	v_pk_mul_f32 v[48:49], v[28:29], v[48:49]
	v_pk_mul_f32 v[50:51], v[30:31], v[50:51]
	global_store_dwordx4 v[52:53], v[48:51], off
	s_nop 1
	v_pk_mul_f32 v[48:49], v[80:81], v[84:85] op_sel_hi:[1,0]
	v_pk_mul_f32 v[50:51], v[62:63], v[84:85] op_sel_hi:[1,0]
	v_pk_mul_f32 v[48:49], v[24:25], v[48:49]
	v_pk_mul_f32 v[50:51], v[26:27], v[50:51]
	global_store_dwordx4 v[52:53], v[48:51], off offset:16
	s_cmpk_lt_u32 s44, 0x5000
	s_cselect_b32 s46, 0x800, 0
	s_addk_i32 s46, 0x800
	s_add_i32 s44, s44, s46
	s_cmpk_lt_u32 s44, 0x5000
	s_cselect_b32 s46, 0x800, 0
	s_addk_i32 s46, 0x800
	s_add_i32 s44, s44, s46
	s_cmpk_le_u32 s44, 0x87ff
	s_cbranch_scc0 .Lfin2_noa
	s_mov_b32 s46, s44
	v_mov_b32_e32 v110, s46
	v_ashrrev_i32_e32 v111, 31, v110
	v_add_u32_e32 v100, 0xffff8000, v110
	v_cmp_gt_i32_e32 vcc, s3, v110
	v_lshlrev_b64 v[48:49], 12, v[110:111]
	v_mov_b32_e32 v101, s11
	v_mov_b32_e32 v47, s9
	v_mov_b32_e32 v64, s10
	v_mov_b32_e32 v66, s8
	v_cndmask_b32_e32 v63, 0, v111, vcc
	v_cndmask_b32_e32 v62, v100, v110, vcc
	v_lshl_add_u64 v[60:61], v[34:35], 0, v[48:49]
	v_cndmask_b32_e32 v65, v101, v47, vcc
	v_cndmask_b32_e32 v64, v64, v66, vcc
	v_lshlrev_b64 v[66:67], 13, v[62:63]
	global_load_dwordx4 v[48:51], v[60:61], off
	global_load_dwordx4 v[52:55], v[60:61], off offset:1024
	v_lshl_add_u64 v[88:89], v[64:65], 0, v[66:67]
	v_lshl_add_u64 v[80:81], v[88:89], 0, v[32:33]
	global_load_dwordx4 v[56:59], v[60:61], off offset:2048
	global_load_dwordx4 v[60:63], v[60:61], off offset:3072
	s_nop 0
	global_load_dwordx4 v[64:67], v[80:81], off
	global_load_dwordx4 v[68:71], v[80:81], off offset:16
	global_load_dwordx4 v[72:75], v[80:81], off offset:2048
	global_load_dwordx4 v[76:79], v[80:81], off offset:2064
	v_lshl_add_u64 v[90:91], v[88:89], 0, v[36:37]
	global_load_dwordx4 v[80:83], v[90:91], off
	global_load_dwordx4 v[84:87], v[90:91], off offset:16
	v_lshl_add_u64 v[96:97], v[88:89], 0, v[38:39]
	global_load_dwordx4 v[88:91], v[96:97], off
	global_load_dwordx4 v[92:95], v[96:97], off offset:16
	s_branch .Lfin2_b

; __device__ __forceinline__ float bf_lo(unsigned u) { return __uint_as_float(u << 16); }
; __device__ __forceinline__ float bf_hi(unsigned u) { return __uint_as_float(u & 0xffff0000u); }
; __device__ __forceinline__ void phase_final(const Params& p) {
;     ...
;         for (int i = 0; i < 4; ++i) { const int c = i * 512 + lane * 8; v[i] = *(const u32x4*)(yr + c); y0[i] = *(const f32x4*)(xi + c); y1[i] = *(const f32x4*)(xi + c + 4); }
; #pragma unroll
;         for (int i = 0; i < 4; ++i) {
;             y0[i] += (f32x4){bf_lo(v[i].x), bf_hi(v[i].x), bf_lo(v[i].y), bf_hi(v[i].y)}; y1[i] += (f32x4){bf_lo(v[i].z), bf_hi(v[i].z), bf_lo(v[i].w), bf_hi(v[i].w)};
;             ss += y0[i][0] * y0[i][0] + y0[i][1] * y0[i][1] + y0[i][2] * y0[i][2] + y0[i][3] * y0[i][3] + y1[i][0] * y1[i][0] + y1[i][1] * y1[i][1] + y1[i][2] * y1[i][2] + y1[i][3] * y1[i][3]; }
;         ss = wave_sum(ss);
.Lfin2_b:
	s_cmpk_le_u32 s45, 0x87ff
	s_cbranch_scc0 .Lfin2_done
	s_waitcnt vmcnt(31)
	v_lshlrev_b32_e32 v196, 16, v148
	v_and_b32_e32 v197, 0xffff0000, v148
	v_lshlrev_b32_e32 v148, 16, v149
	v_and_b32_e32 v149, 0xffff0000, v149
	v_lshlrev_b32_e32 v198, 16, v150
	v_and_b32_e32 v199, 0xffff0000, v150
	v_lshlrev_b32_e32 v150, 16, v151
	v_and_b32_e32 v151, 0xffff0000, v151
	s_waitcnt vmcnt(30)
	v_lshlrev_b32_e32 v200, 16, v152
	v_and_b32_e32 v201, 0xffff0000, v152
	v_lshlrev_b32_e32 v202, 16, v154
	v_and_b32_e32 v203, 0xffff0000, v154
	v_lshlrev_b32_e32 v154, 16, v155
	v_and_b32_e32 v155, 0xffff0000, v155
	s_waitcnt vmcnt(27)
	v_pk_add_f32 v[148:149], v[166:167], v[148:149]
	v_pk_add_f32 v[164:165], v[164:165], v[196:197]
	s_waitcnt vmcnt(26)
	v_pk_add_f32 v[166:167], v[170:171], v[150:151]
	s_waitcnt vmcnt(25)
	v_pk_add_f32 v[170:171], v[172:173], v[200:201]
	v_lshlrev_b32_e32 v152, 16, v153
	v_and_b32_e32 v153, 0xffff0000, v153
	s_waitcnt vmcnt(24)
	v_pk_add_f32 v[154:155], v[178:179], v[154:155]
	v_mov_b32_e32 v178, v165
	v_mov_b32_e32 v179, v171
	v_lshlrev_b32_e32 v204, 16, v156
	v_and_b32_e32 v205, 0xffff0000, v156
	v_pk_add_f32 v[152:153], v[174:175], v[152:153]
	v_mov_b32_e32 v150, v164
	v_mov_b32_e32 v151, v170
	v_pk_mul_f32 v[178:179], v[178:179], v[178:179]
	v_lshlrev_b32_e32 v156, 16, v157
	v_and_b32_e32 v157, 0xffff0000, v157
	s_waitcnt vmcnt(23)
	v_pk_add_f32 v[174:175], v[180:181], v[204:205]
	v_mov_b32_e32 v180, v148
	v_mov_b32_e32 v181, v152
	v_pk_fma_f32 v[150:151], v[150:151], v[150:151], v[178:179]
	v_lshlrev_b32_e32 v206, 16, v158
	v_and_b32_e32 v207, 0xffff0000, v158
	v_lshlrev_b32_e32 v208, 16, v160
	v_and_b32_e32 v209, 0xffff0000, v160
	v_pk_add_f32 v[168:169], v[168:169], v[198:199]
	v_pk_add_f32 v[172:173], v[176:177], v[202:203]
	v_pk_add_f32 v[156:157], v[182:183], v[156:157]
	v_mov_b32_e32 v182, v149
	v_mov_b32_e32 v183, v153
	v_pk_fma_f32 v[150:151], v[180:181], v[180:181], v[150:151]
	s_waitcnt vmcnt(22)
	v_pk_add_f32 v[176:177], v[184:185], v[206:207]
	v_mov_b32_e32 v184, v168
	v_mov_b32_e32 v185, v172
	v_pk_fma_f32 v[150:151], v[182:183], v[182:183], v[150:151]
	s_waitcnt vmcnt(21)
	v_pk_add_f32 v[178:179], v[188:189], v[208:209]
	v_lshlrev_b32_e32 v160, 16, v161
	v_pk_fma_f32 v[150:151], v[184:185], v[184:185], v[150:151]
	v_and_b32_e32 v161, 0xffff0000, v161
	v_mov_b32_e32 v184, v175
	v_mov_b32_e32 v185, v179
	v_pk_add_f32 v[160:161], v[190:191], v[160:161]
	v_mov_b32_e32 v182, v174
	v_mov_b32_e32 v183, v178
	v_pk_mul_f32 v[184:185], v[184:185], v[184:185]
	v_lshlrev_b32_e32 v180, 16, v162
	v_and_b32_e32 v181, 0xffff0000, v162
	v_pk_fma_f32 v[182:183], v[182:183], v[182:183], v[184:185]
	v_mov_b32_e32 v184, v156
	v_mov_b32_e32 v185, v160
	v_lshlrev_b32_e32 v158, 16, v159
	v_and_b32_e32 v159, 0xffff0000, v159
	s_waitcnt vmcnt(20)
	v_pk_add_f32 v[180:181], v[192:193], v[180:181]
	v_pk_fma_f32 v[182:183], v[184:185], v[184:185], v[182:183]
	v_mov_b32_e32 v184, v157
	v_mov_b32_e32 v185, v161
	v_pk_add_f32 v[158:159], v[186:187], v[158:159]
	v_mov_b32_e32 v186, v169
	v_mov_b32_e32 v187, v173
	v_lshlrev_b32_e32 v162, 16, v163
	v_and_b32_e32 v163, 0xffff0000, v163
	v_pk_fma_f32 v[182:183], v[184:185], v[184:185], v[182:183]
	v_mov_b32_e32 v184, v176
	v_mov_b32_e32 v185, v180
	v_mov_b32_e32 v196, v166
	v_mov_b32_e32 v197, v154
	v_pk_fma_f32 v[150:151], v[186:187], v[186:187], v[150:151]
	v_pk_add_f32 v[162:163], v[194:195], v[162:163]
	v_pk_fma_f32 v[182:183], v[184:185], v[184:185], v[182:183]
	v_mov_b32_e32 v184, v177
	v_mov_b32_e32 v185, v181
	v_mov_b32_e32 v198, v167
	v_mov_b32_e32 v199, v155
	v_pk_fma_f32 v[150:151], v[196:197], v[196:197], v[150:151]
	v_pk_fma_f32 v[182:183], v[184:185], v[184:185], v[182:183]
	v_mov_b32_e32 v184, v158
	v_mov_b32_e32 v185, v162
	v_pk_fma_f32 v[150:151], v[198:199], v[198:199], v[150:151]
	v_pk_fma_f32 v[182:183], v[184:185], v[184:185], v[182:183]
	v_mov_b32_e32 v184, v159
	v_mov_b32_e32 v185, v163
	v_pk_fma_f32 v[182:183], v[184:185], v[184:185], v[182:183]
	v_add_f32_e32 v147, v150, v151
	v_add_f32_e32 v147, v147, v182
	v_add_f32_e32 v147, v147, v183
	ds_bpermute_b32 v150, v40, v147
	s_waitcnt lgkmcnt(0)
	v_add_f32_e32 v147, v147, v150
	ds_bpermute_b32 v150, v41, v147
	s_waitcnt lgkmcnt(0)
	v_add_f32_e32 v147, v147, v150
	ds_bpermute_b32 v150, v42, v147
	s_waitcnt lgkmcnt(0)
	v_add_f32_e32 v147, v147, v150
	ds_bpermute_b32 v150, v43, v147
	s_waitcnt lgkmcnt(0)
	v_add_f32_e32 v147, v147, v150
	ds_bpermute_b32 v150, v44, v147
	s_waitcnt lgkmcnt(0)
	v_add_f32_e32 v147, v147, v150
	ds_bpermute_b32 v150, v45, v147
	s_waitcnt lgkmcnt(0)
; __device__ __forceinline__ void phase_final(const Params& p) {
;     ...
;             ss += y0[i][0] * y0[i][0] + y0[i][1] * y0[i][1] + y0[i][2] * y0[i][2] + y0[i][3] * y0[i][3] + y1[i][0] * y1[i][0] + y1[i][1] * y1[i][1] + y1[i][2] * y1[i][2] + y1[i][3] * y1[i][3]; }
;         ss = wave_sum(ss);
;         const float rs = rsqrtf(ss * (1.0f / DM) + 1e-6f);
; #pragma unroll
;         for (int i = 0; i < 4; ++i) { const int c = i * 512 + lane * 8;
;             *(f32x4*)(xr + c) = y0[i] * rs * fg0[i]; *(f32x4*)(xr + c + 4) = y1[i] * rs * fg1[i]; }
;     }
	v_add_f32_e32 v147, v147, v150
	v_fmamk_f32 v147, v147, 0x3a000000, v46
	v_mul_f32_e32 v150, 0x4b800000, v147
	v_cmp_gt_f32_e32 vcc, s4, v147
	s_nop 1
	v_cndmask_b32_e32 v147, v147, v150, vcc
	v_rsq_f32_e32 v147, v147
	v_lshlrev_b64 v[150:151], 13, v[210:211]
	v_lshl_add_u64 v[182:183], s[6:7], 0, v[150:151]
	v_mul_f32_e32 v150, 0x45800000, v147
	v_cndmask_b32_e32 v184, v147, v150, vcc
	v_pk_mul_f32 v[164:165], v[164:165], v[184:185] op_sel_hi:[1,0]
	v_pk_mul_f32 v[148:149], v[148:149], v[184:185] op_sel_hi:[1,0]
	v_pk_mul_f32 v[150:151], v[6:7], v[148:149]
	v_pk_mul_f32 v[148:149], v[4:5], v[164:165]
	v_lshl_add_u64 v[164:165], v[182:183], 0, v[32:33]
	global_store_dwordx4 v[164:165], v[148:151], off
	s_nop 0
	s_nop 0
	v_pk_mul_f32 v[148:149], v[168:169], v[184:185] op_sel_hi:[1,0]
	v_pk_mul_f32 v[150:151], v[166:167], v[184:185] op_sel_hi:[1,0]
	v_pk_mul_f32 v[148:149], v[0:1], v[148:149]
	v_pk_mul_f32 v[150:151], v[2:3], v[150:151]
	global_store_dwordx4 v[164:165], v[148:151], off offset:16
	s_nop 1
	v_pk_mul_f32 v[148:149], v[170:171], v[184:185] op_sel_hi:[1,0]
	v_pk_mul_f32 v[150:151], v[152:153], v[184:185] op_sel_hi:[1,0]
	v_pk_mul_f32 v[148:149], v[12:13], v[148:149]
	v_pk_mul_f32 v[150:151], v[14:15], v[150:151]
	global_store_dwordx4 v[164:165], v[148:151], off offset:2048
	v_lshl_add_u64 v[152:153], v[182:183], 0, v[36:37]
	s_nop 0
	v_pk_mul_f32 v[148:149], v[172:173], v[184:185] op_sel_hi:[1,0]
	v_pk_mul_f32 v[150:151], v[154:155], v[184:185] op_sel_hi:[1,0]
	v_pk_mul_f32 v[148:149], v[8:9], v[148:149]
	v_pk_mul_f32 v[150:151], v[10:11], v[150:151]
	global_store_dwordx4 v[164:165], v[148:151], off offset:2064
	s_nop 1
	v_pk_mul_f32 v[148:149], v[174:175], v[184:185] op_sel_hi:[1,0]
	v_pk_mul_f32 v[150:151], v[156:157], v[184:185] op_sel_hi:[1,0]
	v_pk_mul_f32 v[148:149], v[20:21], v[148:149]
	v_pk_mul_f32 v[150:151], v[22:23], v[150:151]
	global_store_dwordx4 v[152:153], v[148:151], off
	s_nop 1
	v_pk_mul_f32 v[148:149], v[176:177], v[184:185] op_sel_hi:[1,0]
	v_pk_mul_f32 v[150:151], v[158:159], v[184:185] op_sel_hi:[1,0]
	v_pk_mul_f32 v[148:149], v[16:17], v[148:149]
	v_pk_mul_f32 v[150:151], v[18:19], v[150:151]
	global_store_dwordx4 v[152:153], v[148:151], off offset:16
	v_lshl_add_u64 v[152:153], v[182:183], 0, v[38:39]
	s_nop 0
	v_pk_mul_f32 v[148:149], v[178:179], v[184:185] op_sel_hi:[1,0]
	v_pk_mul_f32 v[150:151], v[160:161], v[184:185] op_sel_hi:[1,0]
	v_pk_mul_f32 v[148:149], v[28:29], v[148:149]
	v_pk_mul_f32 v[150:151], v[30:31], v[150:151]
	global_store_dwordx4 v[152:153], v[148:151], off
	s_nop 1
	v_pk_mul_f32 v[148:149], v[180:181], v[184:185] op_sel_hi:[1,0]
	v_pk_mul_f32 v[150:151], v[162:163], v[184:185] op_sel_hi:[1,0]
	v_pk_mul_f32 v[148:149], v[24:25], v[148:149]
	v_pk_mul_f32 v[150:151], v[26:27], v[150:151]
	global_store_dwordx4 v[152:153], v[148:151], off offset:16
	s_cmpk_lt_u32 s45, 0x5000
	s_cselect_b32 s46, 0x800, 0
	s_addk_i32 s46, 0x800
	s_add_i32 s45, s45, s46
	s_cmpk_lt_u32 s45, 0x5000
	s_cselect_b32 s46, 0x800, 0
	s_addk_i32 s46, 0x800
	s_add_i32 s45, s45, s46
	s_cmpk_le_u32 s45, 0x87ff
	s_cbranch_scc0 .Lfin2_nob
	s_mov_b32 s46, s45
	v_mov_b32_e32 v210, s46
	v_ashrrev_i32_e32 v211, 31, v210
	v_add_u32_e32 v200, 0xffff8000, v210
	v_cmp_gt_i32_e32 vcc, s3, v210
	v_lshlrev_b64 v[148:149], 12, v[210:211]
	v_mov_b32_e32 v201, s11
	v_mov_b32_e32 v147, s9
	v_mov_b32_e32 v164, s10
	v_mov_b32_e32 v166, s8
	v_cndmask_b32_e32 v163, 0, v211, vcc
	v_cndmask_b32_e32 v162, v200, v210, vcc
	v_lshl_add_u64 v[160:161], v[34:35], 0, v[148:149]
	v_cndmask_b32_e32 v165, v201, v147, vcc
	v_cndmask_b32_e32 v164, v164, v166, vcc
	v_lshlrev_b64 v[166:167], 13, v[162:163]
	global_load_dwordx4 v[148:151], v[160:161], off
	global_load_dwordx4 v[152:155], v[160:161], off offset:1024
	v_lshl_add_u64 v[188:189], v[164:165], 0, v[166:167]
	v_lshl_add_u64 v[180:181], v[188:189], 0, v[32:33]
	global_load_dwordx4 v[156:159], v[160:161], off offset:2048
	global_load_dwordx4 v[160:163], v[160:161], off offset:3072
	s_nop 0
	global_load_dwordx4 v[164:167], v[180:181], off
	global_load_dwordx4 v[168:171], v[180:181], off offset:16
	global_load_dwordx4 v[172:175], v[180:181], off offset:2048
	global_load_dwordx4 v[176:179], v[180:181], off offset:2064
	v_lshl_add_u64 v[190:191], v[188:189], 0, v[36:37]
	global_load_dwordx4 v[180:183], v[190:191], off
	global_load_dwordx4 v[184:187], v[190:191], off offset:16
	v_lshl_add_u64 v[196:197], v[188:189], 0, v[38:39]
	global_load_dwordx4 v[188:191], v[196:197], off
	global_load_dwordx4 v[192:195], v[196:197], off offset:16
	s_branch .Lfin2_c

; __device__ __forceinline__ void phase_final(const Params& p) {
;     ...
;     for (int row = blockIdx.x * 8 + wid; row < MT; row += gridDim.x * 8) {
.Lfin2_c:
	s_cmpk_le_u32 s44, 0x87ff
	s_cbranch_scc1 .Lfin2_loop
.Lfin2_done:
.LBB0_619:
	s_endpgm
